# MLA latent attention loop: K fragments of a 32-key tile prefetched into 48 spare VGPRs (counted lgkmcnt ladder), second V half read early
# baseline (speedup 1.0000x reference)
.LBB0_786:
	s_bitcmp1_b32 s2, 0
	s_cselect_b32 s2, 0xa000, 0
	v_add_u32_e32 v96, s2, v95
	ds_read_b128 v[172:175], v96
	ds_read_b128 v[176:179], v96 offset:1024
	ds_read_b128 v[188:191], v96 offset:2048
	ds_read_b128 v[192:195], v96 offset:3072
	ds_read_b128 v[198:201], v96 offset:4096
	ds_read_b128 v[202:205], v96 offset:5120
	ds_read_b128 v[206:209], v96 offset:6144
	ds_read_b128 v[218:221], v96 offset:7168
	ds_read_b128 v[222:225], v96 offset:8192
	ds_read_b128 v[226:229], v96 offset:9216
	ds_read_b128 v[230:233], v96 offset:10240
	ds_read_b128 v[234:237], v96 offset:11264
	s_waitcnt lgkmcnt(11)
	v_mfma_f32_32x32x16_bf16 v[64:79], v[172:175], v[82:85], 0
	s_waitcnt lgkmcnt(10)
	v_mfma_f32_32x32x16_bf16 v[64:79], v[176:179], v[86:89], v[64:79]
	s_waitcnt lgkmcnt(9)
	v_mfma_f32_32x32x16_bf16 v[64:79], v[188:191], v[90:93], v[64:79]
	s_waitcnt lgkmcnt(8)
	v_mfma_f32_32x32x16_bf16 v[64:79], v[192:195], v[112:115], v[64:79]
	s_waitcnt lgkmcnt(7)
	v_mfma_f32_32x32x16_bf16 v[64:79], v[198:201], v[116:119], v[64:79]
	s_waitcnt lgkmcnt(6)
	v_mfma_f32_32x32x16_bf16 v[64:79], v[202:205], v[120:123], v[64:79]
	s_waitcnt lgkmcnt(5)
	v_mfma_f32_32x32x16_bf16 v[64:79], v[206:209], v[124:127], v[64:79]
	s_waitcnt lgkmcnt(4)
	v_mfma_f32_32x32x16_bf16 v[64:79], v[218:221], v[128:131], v[64:79]
	s_waitcnt lgkmcnt(3)
	v_mfma_f32_32x32x16_bf16 v[64:79], v[222:225], v[132:135], v[64:79]
	s_waitcnt lgkmcnt(2)
	v_mfma_f32_32x32x16_bf16 v[64:79], v[226:229], v[136:139], v[64:79]
	s_waitcnt lgkmcnt(1)
	v_mfma_f32_32x32x16_bf16 v[64:79], v[230:233], v[140:143], v[64:79]
	s_waitcnt lgkmcnt(0)
	v_mfma_f32_32x32x16_bf16 v[64:79], v[234:237], v[144:147], v[64:79]
	ds_read_b128 v[172:175], v96 offset:20480
	ds_read_b128 v[176:179], v96 offset:21504
	ds_read_b128 v[188:191], v96 offset:22528
	ds_read_b128 v[192:195], v96 offset:23552
	ds_read_b128 v[198:201], v96 offset:24576
	ds_read_b128 v[202:205], v96 offset:25600
	ds_read_b128 v[206:209], v96 offset:26624
	ds_read_b128 v[218:221], v96 offset:27648
	ds_read_b128 v[222:225], v96 offset:28672
	ds_read_b128 v[226:229], v96 offset:29696
	ds_read_b128 v[230:233], v96 offset:30720
	ds_read_b128 v[234:237], v96 offset:31744
	ds_read_b128 v[148:151], v96 offset:12288
	ds_read_b128 v[106:109], v96 offset:13312
	ds_read_b128 v[98:101], v96 offset:14336
	ds_read_b128 v[102:105], v96 offset:15360
	s_nop 7
	v_max_f32_e32 v110, v65, v65
	v_max_f32_e32 v111, v64, v64
	v_max_f32_e32 v110, v111, v110
	v_max3_f32 v110, v110, v66, v67
	v_max3_f32 v110, v110, v68, v69
	v_max3_f32 v110, v110, v70, v71
	v_max3_f32 v110, v110, v72, v73
	v_max3_f32 v110, v110, v74, v75
	v_max3_f32 v110, v110, v76, v77
	v_max3_f32 v110, v110, v78, v79
	v_mov_b32_e32 v111, v110
	s_nop 1
	v_permlane32_swap_b32_e32 v110, v111
	v_max_f32_e32 v111, v111, v111
	v_max_f32_e32 v110, v110, v110
	v_max_f32_e32 v110, v110, v111
	v_mul_f32_e32 v111, 0x3dd53b94, v110
	v_add_f32_e32 v110, 0x41000000, v80
	v_cmp_le_f32_e32 vcc, v111, v110
	s_cmp_eq_u64 vcc, exec
	s_cbranch_scc1 .LBB0_788
	v_max_f32_e32 v110, v111, v111
	v_max_f32_e32 v111, v80, v80
	v_max_f32_e32 v111, v111, v110
	v_sub_f32_e32 v80, v80, v111
	v_exp_f32_e32 v80, v80
	v_add_f32_e32 v110, 0x41000000, v111
	v_mul_f32_e32 v81, v81, v80
	v_pk_mul_f32 v[62:63], v[62:63], v[80:81] op_sel_hi:[1,0]
	v_pk_mul_f32 v[60:61], v[60:61], v[80:81] op_sel_hi:[1,0]
	v_pk_mul_f32 v[58:59], v[58:59], v[80:81] op_sel_hi:[1,0]
	v_pk_mul_f32 v[56:57], v[56:57], v[80:81] op_sel_hi:[1,0]
	v_pk_mul_f32 v[54:55], v[54:55], v[80:81] op_sel_hi:[1,0]
	v_pk_mul_f32 v[52:53], v[52:53], v[80:81] op_sel_hi:[1,0]
	v_pk_mul_f32 v[50:51], v[50:51], v[80:81] op_sel_hi:[1,0]
	v_pk_mul_f32 v[48:49], v[48:49], v[80:81] op_sel_hi:[1,0]
	v_pk_mul_f32 v[46:47], v[46:47], v[80:81] op_sel_hi:[1,0]
	v_pk_mul_f32 v[44:45], v[44:45], v[80:81] op_sel_hi:[1,0]
	v_pk_mul_f32 v[42:43], v[42:43], v[80:81] op_sel_hi:[1,0]
	v_pk_mul_f32 v[40:41], v[40:41], v[80:81] op_sel_hi:[1,0]
	v_pk_mul_f32 v[38:39], v[38:39], v[80:81] op_sel_hi:[1,0]
	v_pk_mul_f32 v[36:37], v[36:37], v[80:81] op_sel_hi:[1,0]
	v_pk_mul_f32 v[34:35], v[34:35], v[80:81] op_sel_hi:[1,0]
	v_pk_mul_f32 v[32:33], v[32:33], v[80:81] op_sel_hi:[1,0]
	v_pk_mul_f32 v[30:31], v[30:31], v[80:81] op_sel_hi:[1,0]
	v_pk_mul_f32 v[28:29], v[28:29], v[80:81] op_sel_hi:[1,0]
	v_pk_mul_f32 v[26:27], v[26:27], v[80:81] op_sel_hi:[1,0]
	v_pk_mul_f32 v[24:25], v[24:25], v[80:81] op_sel_hi:[1,0]
	v_pk_mul_f32 v[22:23], v[22:23], v[80:81] op_sel_hi:[1,0]
	v_pk_mul_f32 v[20:21], v[20:21], v[80:81] op_sel_hi:[1,0]
	v_pk_mul_f32 v[18:19], v[18:19], v[80:81] op_sel_hi:[1,0]
	v_pk_mul_f32 v[16:17], v[16:17], v[80:81] op_sel_hi:[1,0]
	v_pk_mul_f32 v[14:15], v[14:15], v[80:81] op_sel_hi:[1,0]
	v_pk_mul_f32 v[12:13], v[12:13], v[80:81] op_sel_hi:[1,0]
	v_pk_mul_f32 v[10:11], v[10:11], v[80:81] op_sel_hi:[1,0]
	v_pk_mul_f32 v[8:9], v[8:9], v[80:81] op_sel_hi:[1,0]
	v_pk_mul_f32 v[6:7], v[6:7], v[80:81] op_sel_hi:[1,0]
	v_pk_mul_f32 v[4:5], v[4:5], v[80:81] op_sel_hi:[1,0]
	v_pk_mul_f32 v[2:3], v[2:3], v[80:81] op_sel_hi:[1,0]
	v_pk_mul_f32 v[0:1], v[0:1], v[80:81] op_sel_hi:[1,0]
	v_mov_b32_e32 v80, v111
.LBB0_788:
	v_fma_f32 v64, v64, s80, -v80
	v_exp_f32_e32 v64, v64
	v_fma_f32 v65, v65, s80, -v80
	v_exp_f32_e32 v65, v65
	v_fma_f32 v66, v66, s80, -v80
	v_exp_f32_e32 v66, v66
	v_fma_f32 v67, v67, s80, -v80
	v_exp_f32_e32 v67, v67
	v_fma_f32 v68, v68, s80, -v80
	v_add_f32_e32 v111, 0, v64
	v_exp_f32_e32 v68, v68
	v_fma_f32 v69, v69, s80, -v80
	v_add_f32_e32 v111, v65, v111
	v_exp_f32_e32 v69, v69
	v_fma_f32 v70, v70, s80, -v80
	v_add_f32_e32 v111, v66, v111
	v_exp_f32_e32 v70, v70
	v_fma_f32 v71, v71, s80, -v80
	v_add_f32_e32 v111, v67, v111
	v_exp_f32_e32 v71, v71
	v_fma_f32 v72, v72, s80, -v80
	v_add_f32_e32 v111, v68, v111
	v_exp_f32_e32 v159, v72
	v_add_f32_e32 v111, v69, v111
	v_add_f32_e32 v111, v70, v111
	v_add_f32_e32 v111, v71, v111
	v_fma_f32 v73, v73, s80, -v80
	v_add_f32_e32 v72, v159, v111
	v_exp_f32_e32 v111, v73
	v_fma_f32 v73, v74, s80, -v80
	v_exp_f32_e32 v165, v73
	v_fma_f32 v73, v75, s80, -v80
	v_exp_f32_e32 v166, v73
	v_fma_f32 v73, v76, s80, -v80
	v_exp_f32_e32 v167, v73
	v_fma_f32 v73, v77, s80, -v80
	v_add_f32_e32 v72, v111, v72
	v_exp_f32_e32 v168, v73
	v_fma_f32 v73, v78, s80, -v80
	v_add_f32_e32 v72, v165, v72
	v_exp_f32_e32 v169, v73
	v_fma_f32 v73, v79, s80, -v80
	v_add_f32_e32 v72, v166, v72
	v_exp_f32_e32 v170, v73
	v_add_f32_e32 v72, v167, v72
	v_cvt_pk_bf16_f32 v64, v64, v65
	v_cvt_pk_bf16_f32 v65, v66, v67
	v_cvt_pk_bf16_f32 v66, v68, v69
	v_cvt_pk_bf16_f32 v67, v70, v71
	v_add_f32_e32 v72, v168, v72
	v_add_f32_e32 v72, v169, v72
	s_waitcnt lgkmcnt(0)
	v_mfma_f32_32x32x16_bf16 v[48:63], v[148:151], v[64:67], v[48:63]
	v_add_f32_e32 v72, v170, v72
	v_mov_b32_e32 v73, v72
	s_nop 1
	v_permlane32_swap_b32_e32 v72, v73
	v_add_f32_e32 v72, v72, v73
	v_add_f32_e32 v81, v81, v72
	ds_read_b128 v[238:241], v96 offset:16384
	ds_read_b128 v[68:71], v96 offset:17408
	ds_read_b128 v[72:75], v96 offset:18432
	ds_read_b128 v[76:79], v96 offset:19456
	v_mfma_f32_32x32x16_bf16 v[32:47], v[106:109], v[64:67], v[32:47]
	v_mfma_f32_32x32x16_bf16 v[16:31], v[98:101], v[64:67], v[16:31]
	v_cvt_pk_bf16_f32 v98, v159, v111
	v_cvt_pk_bf16_f32 v99, v165, v166
	v_cvt_pk_bf16_f32 v100, v167, v168
	v_cvt_pk_bf16_f32 v101, v169, v170
	v_mfma_f32_32x32x16_bf16 v[0:15], v[102:105], v[64:67], v[0:15]
	s_waitcnt lgkmcnt(0)
	v_mfma_f32_32x32x16_bf16 v[48:63], v[238:241], v[98:101], v[48:63]
	v_mfma_f32_32x32x16_bf16 v[32:47], v[68:71], v[98:101], v[32:47]
	v_mfma_f32_32x32x16_bf16 v[16:31], v[72:75], v[98:101], v[16:31]
	v_mfma_f32_32x32x16_bf16 v[0:15], v[76:79], v[98:101], v[0:15]
	v_mfma_f32_32x32x16_bf16 v[64:79], v[172:175], v[82:85], 0
	v_mfma_f32_32x32x16_bf16 v[64:79], v[176:179], v[86:89], v[64:79]
	v_mfma_f32_32x32x16_bf16 v[64:79], v[188:191], v[90:93], v[64:79]
	v_mfma_f32_32x32x16_bf16 v[64:79], v[192:195], v[112:115], v[64:79]
	v_mfma_f32_32x32x16_bf16 v[64:79], v[198:201], v[116:119], v[64:79]
	v_mfma_f32_32x32x16_bf16 v[64:79], v[202:205], v[120:123], v[64:79]
	v_mfma_f32_32x32x16_bf16 v[64:79], v[206:209], v[124:127], v[64:79]
	v_mfma_f32_32x32x16_bf16 v[64:79], v[218:221], v[128:131], v[64:79]
	v_mfma_f32_32x32x16_bf16 v[64:79], v[222:225], v[132:135], v[64:79]
	v_mfma_f32_32x32x16_bf16 v[64:79], v[226:229], v[136:139], v[64:79]
	v_mfma_f32_32x32x16_bf16 v[64:79], v[230:233], v[140:143], v[64:79]
	v_mfma_f32_32x32x16_bf16 v[64:79], v[234:237], v[144:147], v[64:79]
	ds_read_b128 v[148:151], v96 offset:32768
	ds_read_b128 v[106:109], v96 offset:33792
	ds_read_b128 v[98:101], v96 offset:34816
	ds_read_b128 v[102:105], v96 offset:35840
	s_nop 7
	v_max_f32_e32 v111, v65, v65
	v_max_f32_e32 v159, v64, v64
	v_max_f32_e32 v111, v159, v111
	v_max3_f32 v111, v111, v66, v67
	v_max3_f32 v111, v111, v68, v69
	v_max3_f32 v111, v111, v70, v71
	v_max3_f32 v111, v111, v72, v73
	v_max3_f32 v111, v111, v74, v75
	v_max3_f32 v111, v111, v76, v77
	v_max3_f32 v111, v111, v78, v79
	v_mov_b32_e32 v159, v111
	s_nop 1
	v_permlane32_swap_b32_e32 v111, v159
	v_max_f32_e32 v159, v159, v159
	v_max_f32_e32 v111, v111, v111
	v_max_f32_e32 v111, v111, v159
	v_mul_f32_e32 v111, 0x3dd53b94, v111
	v_cmp_le_f32_e32 vcc, v111, v110
	s_cmp_eq_u64 vcc, exec
	s_cbranch_scc1 .LBB0_790
	v_max_f32_e32 v110, v111, v111
	v_max_f32_e32 v111, v80, v80
	v_max_f32_e32 v111, v111, v110
	v_sub_f32_e32 v80, v80, v111
	v_exp_f32_e32 v80, v80
	v_xor_b32_e32 v110, 0x80000000, v111
	v_mul_f32_e32 v81, v81, v80
	v_pk_mul_f32 v[62:63], v[62:63], v[80:81] op_sel_hi:[1,0]
	v_pk_mul_f32 v[60:61], v[60:61], v[80:81] op_sel_hi:[1,0]
	v_pk_mul_f32 v[58:59], v[58:59], v[80:81] op_sel_hi:[1,0]
	v_pk_mul_f32 v[56:57], v[56:57], v[80:81] op_sel_hi:[1,0]
	v_pk_mul_f32 v[54:55], v[54:55], v[80:81] op_sel_hi:[1,0]
	v_pk_mul_f32 v[52:53], v[52:53], v[80:81] op_sel_hi:[1,0]
	v_pk_mul_f32 v[50:51], v[50:51], v[80:81] op_sel_hi:[1,0]
	v_pk_mul_f32 v[48:49], v[48:49], v[80:81] op_sel_hi:[1,0]
	v_pk_mul_f32 v[46:47], v[46:47], v[80:81] op_sel_hi:[1,0]
	v_pk_mul_f32 v[44:45], v[44:45], v[80:81] op_sel_hi:[1,0]
	v_pk_mul_f32 v[42:43], v[42:43], v[80:81] op_sel_hi:[1,0]
	v_pk_mul_f32 v[40:41], v[40:41], v[80:81] op_sel_hi:[1,0]
	v_pk_mul_f32 v[38:39], v[38:39], v[80:81] op_sel_hi:[1,0]
	v_pk_mul_f32 v[36:37], v[36:37], v[80:81] op_sel_hi:[1,0]
	v_pk_mul_f32 v[34:35], v[34:35], v[80:81] op_sel_hi:[1,0]
	v_pk_mul_f32 v[32:33], v[32:33], v[80:81] op_sel_hi:[1,0]
	v_pk_mul_f32 v[30:31], v[30:31], v[80:81] op_sel_hi:[1,0]
	v_pk_mul_f32 v[28:29], v[28:29], v[80:81] op_sel_hi:[1,0]
	v_pk_mul_f32 v[26:27], v[26:27], v[80:81] op_sel_hi:[1,0]
	v_pk_mul_f32 v[24:25], v[24:25], v[80:81] op_sel_hi:[1,0]
	v_pk_mul_f32 v[22:23], v[22:23], v[80:81] op_sel_hi:[1,0]
	v_pk_mul_f32 v[20:21], v[20:21], v[80:81] op_sel_hi:[1,0]
	v_pk_mul_f32 v[18:19], v[18:19], v[80:81] op_sel_hi:[1,0]
	v_pk_mul_f32 v[16:17], v[16:17], v[80:81] op_sel_hi:[1,0]
	v_pk_mul_f32 v[14:15], v[14:15], v[80:81] op_sel_hi:[1,0]
	v_pk_mul_f32 v[12:13], v[12:13], v[80:81] op_sel_hi:[1,0]
	v_pk_mul_f32 v[10:11], v[10:11], v[80:81] op_sel_hi:[1,0]
	v_pk_mul_f32 v[8:9], v[8:9], v[80:81] op_sel_hi:[1,0]
	v_pk_mul_f32 v[6:7], v[6:7], v[80:81] op_sel_hi:[1,0]
	v_pk_mul_f32 v[4:5], v[4:5], v[80:81] op_sel_hi:[1,0]
	v_pk_mul_f32 v[2:3], v[2:3], v[80:81] op_sel_hi:[1,0]
	v_pk_mul_f32 v[0:1], v[0:1], v[80:81] op_sel_hi:[1,0]
	v_mov_b32_e32 v80, v111
	s_branch .LBB0_791

.LBB0_791:
	v_fmamk_f32 v64, v64, 0x3dd53b94, v110
	v_exp_f32_e32 v64, v64
	v_fmamk_f32 v65, v65, 0x3dd53b94, v110
	v_exp_f32_e32 v65, v65
	v_fmamk_f32 v66, v66, 0x3dd53b94, v110
	v_exp_f32_e32 v66, v66
	v_fmamk_f32 v67, v67, 0x3dd53b94, v110
	v_exp_f32_e32 v67, v67
	v_fmamk_f32 v68, v68, 0x3dd53b94, v110
	v_add_f32_e32 v111, 0, v64
	v_exp_f32_e32 v68, v68
	v_fmamk_f32 v69, v69, 0x3dd53b94, v110
	v_add_f32_e32 v111, v65, v111
	v_exp_f32_e32 v69, v69
	v_fmamk_f32 v70, v70, 0x3dd53b94, v110
	v_add_f32_e32 v111, v66, v111
	v_exp_f32_e32 v70, v70
	v_fmamk_f32 v71, v71, 0x3dd53b94, v110
	v_add_f32_e32 v111, v67, v111
	v_exp_f32_e32 v71, v71
	v_fmamk_f32 v72, v72, 0x3dd53b94, v110
	v_add_f32_e32 v111, v68, v111
	v_exp_f32_e32 v159, v72
	v_add_f32_e32 v111, v69, v111
	v_add_f32_e32 v111, v70, v111
	v_add_f32_e32 v111, v71, v111
	v_fmamk_f32 v73, v73, 0x3dd53b94, v110
	v_add_f32_e32 v72, v159, v111
	v_exp_f32_e32 v111, v73
	v_fmamk_f32 v73, v74, 0x3dd53b94, v110
	v_exp_f32_e32 v165, v73
	v_fmamk_f32 v73, v75, 0x3dd53b94, v110
	v_exp_f32_e32 v166, v73
	v_fmamk_f32 v73, v76, 0x3dd53b94, v110
	v_exp_f32_e32 v167, v73
	v_fmamk_f32 v73, v77, 0x3dd53b94, v110
	v_add_f32_e32 v72, v111, v72
	v_exp_f32_e32 v168, v73
	v_fmamk_f32 v73, v78, 0x3dd53b94, v110
	v_add_f32_e32 v72, v165, v72
	v_exp_f32_e32 v169, v73
	v_fmac_f32_e32 v110, 0x3dd53b94, v79
	v_add_f32_e32 v72, v166, v72
	v_exp_f32_e32 v110, v110
	v_add_f32_e32 v72, v167, v72
	v_add_f32_e32 v72, v168, v72
	v_add_f32_e32 v72, v169, v72
	v_add_f32_e32 v72, v110, v72
	v_cvt_pk_bf16_f32 v64, v64, v65
	v_cvt_pk_bf16_f32 v65, v66, v67
	v_cvt_pk_bf16_f32 v66, v68, v69
	v_cvt_pk_bf16_f32 v67, v70, v71
	v_mov_b32_e32 v73, v72
	s_nop 1
	v_permlane32_swap_b32_e32 v72, v73
	s_waitcnt lgkmcnt(0)
	v_mfma_f32_32x32x16_bf16 v[48:63], v[148:151], v[64:67], v[48:63]
	v_add_f32_e32 v72, v72, v73
	v_add_f32_e32 v81, v81, v72
	ds_read_b128 v[238:241], v96 offset:36864
	ds_read_b128 v[68:71], v96 offset:37888
	ds_read_b128 v[72:75], v96 offset:38912
	ds_read_b128 v[76:79], v96 offset:39936
	v_lshl_add_u64 v[160:161], v[160:161], 0, s[26:27]
	v_lshl_add_u64 v[162:163], v[162:163], 0, s[28:29]
	s_cmp_eq_u32 s5, 34
	v_mfma_f32_32x32x16_bf16 v[32:47], v[106:109], v[64:67], v[32:47]
	v_mfma_f32_32x32x16_bf16 v[16:31], v[98:101], v[64:67], v[16:31]
	v_cvt_pk_bf16_f32 v98, v159, v111
	v_cvt_pk_bf16_f32 v99, v165, v166
	v_cvt_pk_bf16_f32 v100, v167, v168
	v_cvt_pk_bf16_f32 v101, v169, v110
	v_mfma_f32_32x32x16_bf16 v[0:15], v[102:105], v[64:67], v[0:15]
	s_waitcnt lgkmcnt(0)
	v_mfma_f32_32x32x16_bf16 v[48:63], v[238:241], v[98:101], v[48:63]
	v_mfma_f32_32x32x16_bf16 v[32:47], v[68:71], v[98:101], v[32:47]
	v_mfma_f32_32x32x16_bf16 v[16:31], v[72:75], v[98:101], v[16:31]
	v_mfma_f32_32x32x16_bf16 v[0:15], v[76:79], v[98:101], v[0:15]
	s_cbranch_scc1 .LBB0_793
	s_mov_b32 s2, s5
	s_branch .LBB0_784
